# PEER load balance: the 512 extra tokens are handled block-cooperatively (2 slices per wave, partial dots combined via LDS), every wave does 66 units per stage
# speedup vs baseline: 1.1758x; 1.0170x over previous
.Lpf_b_rejoin:
	s_waitcnt lgkmcnt(0)
	v_add_f32_e32 v72, v72, v73
	v_fmamk_f32 v72, v72, 0x3a800000, v198
	v_mul_f32_e32 v73, 0x4b800000, v72
	v_cmp_gt_f32_e32 vcc, s35, v72
	s_nop 1
	v_cndmask_b32_e32 v72, v72, v73, vcc
	v_rsq_f32_e32 v72, v72
	s_nop 0
	v_mul_f32_e32 v73, 0x45800000, v72
	v_cndmask_b32_e32 v72, v72, v73, vcc
	v_mul_f32_e32 v72, 0x3b800000, v72
	v_add_u32_e32 v32, 0x100, v143
	ds_read2st64_b32 v[34:35], v32 offset1:1
	ds_read2st64_b32 v[36:37], v32 offset0:2 offset1:3
	s_lshl_b32 s0, s26, 9
	v_add_u32_e32 v33, s0, v202
	s_lshl_b32 s0, s26, 2
	v_add_u32_e32 v38, s0, v204
	s_waitcnt lgkmcnt(0)
	v_lshlrev_b32_e32 v34, 7, v34
	v_lshlrev_b32_e32 v35, 7, v35
	ds_write2st64_b32 v33, v34, v35 offset1:1
	ds_write2st64_b32 v33, v36, v37 offset0:18 offset1:19
	ds_write2st64_b32 v33, v203, v203 offset0:36 offset1:37
	ds_write_b32 v38, v72
	s_add_i32 s26, s26, 1
	s_cmp_lt_i32 s26, 8
	s_cbranch_scc0 .Ll1_last
	v_add_u32_e32 v96, s3, v96
	s_branch .LBB0_1117
.Ll1_last:
	s_cmp_eq_u32 s26, 8
	s_cbranch_scc0 .Ll1_done
	s_add_i32 s0, s2, 0x4000
	v_mov_b32_e32 v96, s0
	s_branch .LBB0_1117
.Ll1_done:
	s_waitcnt lgkmcnt(0)
	v_readlane_b32 s4, v242, 1
	v_readlane_b32 s5, v242, 2
	v_readlane_b32 s6, v243, 47
	v_readlane_b32 s7, v243, 48
	v_readlane_b32 s8, v242, 27
	v_readlane_b32 s9, v242, 28
	v_readlane_b32 s12, v242, 19
	v_readlane_b32 s13, v242, 20
	v_readlane_b32 s14, v243, 6
	v_readlane_b32 s15, v243, 7
	v_readfirstlane_b32 s27, v214
	s_add_i32 s44, s2, 0x4000
	s_add_u32 s10, s8, 0x1000000
	s_addc_u32 s11, s9, 0
	s_mov_b32 s45, s27
	s_lshl_b32 s0, s2, 2
	s_add_i32 s27, s27, s0
	v_and_b32_e32 v188, 7, v218
	v_bfe_u32 v190, v218, 3, 3
	v_lshlrev_b32_e32 v189, 6, v188
	v_lshlrev_b32_e32 v213, 5, v188
	v_lshlrev_b32_e32 v188, 4, v188
	v_lshl_add_u32 v211, v190, 3, v189
	v_lshl_add_u32 v213, v190, 2, v213
	v_bfe_u32 v209, v218, 2, 1
	v_lshlrev_b32_e32 v190, 6, v190
	v_lshlrev_b32_e32 v209, 5, v209
	v_add_u32_e32 v190, v190, v204
	v_add_u32_e32 v190, 0xffffca00, v190
	v_add_u32_e32 v209, v209, v190
	v_add_u32_e32 v209, 0x2400, v209
	s_mov_b32 s38, 0xffff0000
	s_mov_b32 s39, 0xffff0000
	s_mov_b32 s16, 0
.Lpb_slice:
	s_mov_b32 s17, 0
	s_lshr_b32 s0, s16, 1
	s_cmp_eq_u32 s0, s45
	s_cselect_b32 s43, 9, 8
.Lpb_unit:
	s_lshl_b32 s0, s17, 11
	s_add_i32 s0, s0, s27
	s_cmp_eq_u32 s17, 8
	s_cselect_b32 s0, s44, s0
	s_lshl_b32 s1, s16, 9
	s_lshl_b32 s24, s0, 12
	s_add_u32 s24, s24, s1
	s_add_u32 s20, s4, s24
	s_addc_u32 s21, s5, 0
	s_add_u32 s36, s6, s1
	s_addc_u32 s37, s7, 0
	s_lshl_b32 s25, s16, 21
	s_add_u32 s18, s8, s25
	s_addc_u32 s19, s9, 0
	s_lshl_b32 s25, s17, 9
	v_add_u32_e32 v205, s25, v190
	v_add_u32_e32 v210, s25, v209
	s_lshl_b32 s25, s17, 2
	v_add_u32_e32 v206, s25, v204
	ds_read_b128 v[64:67], v205
	ds_read_b128 v[68:71], v205 offset:16
	ds_read_b128 v[72:75], v205 offset:32
	ds_read_b128 v[76:79], v205 offset:48
	ds_read_b32 v208, v206
	global_load_dwordx4 v[80:83], v189, s[20:21]
	global_load_dwordx4 v[84:87], v189, s[20:21] offset:16
	global_load_dwordx4 v[88:91], v189, s[20:21] offset:32
	global_load_dwordx4 v[92:95], v189, s[20:21] offset:48
	global_load_dwordx4 v[96:99], v189, s[36:37]
	global_load_dwordx4 v[100:103], v189, s[36:37] offset:16
	global_load_dwordx4 v[104:107], v189, s[36:37] offset:32
	global_load_dwordx4 v[108:111], v189, s[36:37] offset:48
	s_waitcnt lgkmcnt(1)
	v_add_u32_e32 v64, v64, v188
	v_add_u32_e32 v65, v65, v188
	v_add_u32_e32 v66, v66, v188
	v_add_u32_e32 v67, v67, v188
	v_add_u32_e32 v68, v68, v188
	v_add_u32_e32 v69, v69, v188
	v_add_u32_e32 v70, v70, v188
	v_add_u32_e32 v71, v71, v188
	v_add_u32_e32 v72, v72, v188
	v_add_u32_e32 v73, v73, v188
	v_add_u32_e32 v74, v74, v188
	v_add_u32_e32 v75, v75, v188
	v_add_u32_e32 v76, v76, v188
	v_add_u32_e32 v77, v77, v188
	v_add_u32_e32 v78, v78, v188
	v_add_u32_e32 v79, v79, v188
	global_load_dwordx4 v[0:3], v64, s[18:19]
	global_load_dwordx4 v[4:7], v65, s[18:19]
	global_load_dwordx4 v[8:11], v66, s[18:19]
	global_load_dwordx4 v[12:15], v67, s[18:19]
	global_load_dwordx4 v[16:19], v68, s[18:19]
	global_load_dwordx4 v[20:23], v69, s[18:19]
	global_load_dwordx4 v[24:27], v70, s[18:19]
	global_load_dwordx4 v[28:31], v71, s[18:19]
	global_load_dwordx4 v[32:35], v72, s[18:19]
	global_load_dwordx4 v[36:39], v73, s[18:19]
	global_load_dwordx4 v[40:43], v74, s[18:19]
	global_load_dwordx4 v[44:47], v75, s[18:19]
	global_load_dwordx4 v[48:51], v76, s[18:19]
	global_load_dwordx4 v[52:55], v77, s[18:19]
	global_load_dwordx4 v[56:59], v78, s[18:19]
	global_load_dwordx4 v[60:63], v79, s[18:19]
	s_waitcnt vmcnt(16) lgkmcnt(0)
	v_pk_mul_f32 v[96:97], v[96:97], v[208:209] op_sel_hi:[1,0]
	v_pk_mul_f32 v[98:99], v[98:99], v[208:209] op_sel_hi:[1,0]
	v_pk_mul_f32 v[100:101], v[100:101], v[208:209] op_sel_hi:[1,0]
	v_pk_mul_f32 v[102:103], v[102:103], v[208:209] op_sel_hi:[1,0]
	v_pk_mul_f32 v[104:105], v[104:105], v[208:209] op_sel_hi:[1,0]
	v_pk_mul_f32 v[106:107], v[106:107], v[208:209] op_sel_hi:[1,0]
	v_pk_mul_f32 v[108:109], v[108:109], v[208:209] op_sel_hi:[1,0]
	v_pk_mul_f32 v[110:111], v[110:111], v[208:209] op_sel_hi:[1,0]
	v_pk_mul_f32 v[80:81], v[80:81], v[96:97]
	v_pk_mul_f32 v[82:83], v[82:83], v[98:99]
	v_pk_mul_f32 v[84:85], v[84:85], v[100:101]
	v_pk_mul_f32 v[86:87], v[86:87], v[102:103]
	v_pk_mul_f32 v[88:89], v[88:89], v[104:105]
	v_pk_mul_f32 v[90:91], v[90:91], v[106:107]
	v_pk_mul_f32 v[92:93], v[92:93], v[108:109]
	v_pk_mul_f32 v[94:95], v[94:95], v[110:111]
	s_waitcnt vmcnt(15)
	v_cvt_pk_f32_fp8_e32 v[168:169], v0
	v_cvt_pk_f32_fp8_sdwa v[170:171], v0 src0_sel:WORD_1
	v_cvt_pk_f32_fp8_e32 v[172:173], v1
	v_cvt_pk_f32_fp8_sdwa v[174:175], v1 src0_sel:WORD_1
	v_cvt_pk_f32_fp8_e32 v[176:177], v2
	v_cvt_pk_f32_fp8_sdwa v[178:179], v2 src0_sel:WORD_1
	v_cvt_pk_f32_fp8_e32 v[180:181], v3
	v_cvt_pk_f32_fp8_sdwa v[182:183], v3 src0_sel:WORD_1
	v_pk_mul_f32 v[184:185], v[168:169], v[80:81]
	v_pk_mul_f32 v[186:187], v[170:171], v[82:83]
	v_pk_fma_f32 v[184:185], v[172:173], v[84:85], v[184:185]
	v_pk_fma_f32 v[186:187], v[174:175], v[86:87], v[186:187]
	v_pk_fma_f32 v[184:185], v[176:177], v[88:89], v[184:185]
	v_pk_fma_f32 v[186:187], v[178:179], v[90:91], v[186:187]
	v_pk_fma_f32 v[184:185], v[180:181], v[92:93], v[184:185]
	v_pk_fma_f32 v[186:187], v[182:183], v[94:95], v[186:187]
	v_pk_add_f32 v[184:185], v[184:185], v[186:187]
	v_add_f32_e32 v112, v184, v185
	s_waitcnt vmcnt(14)
	v_cvt_pk_f32_fp8_e32 v[168:169], v4
	v_cvt_pk_f32_fp8_sdwa v[170:171], v4 src0_sel:WORD_1
	v_cvt_pk_f32_fp8_e32 v[172:173], v5
	v_cvt_pk_f32_fp8_sdwa v[174:175], v5 src0_sel:WORD_1
	v_cvt_pk_f32_fp8_e32 v[176:177], v6
	v_cvt_pk_f32_fp8_sdwa v[178:179], v6 src0_sel:WORD_1
	v_cvt_pk_f32_fp8_e32 v[180:181], v7
	v_cvt_pk_f32_fp8_sdwa v[182:183], v7 src0_sel:WORD_1
	v_pk_mul_f32 v[184:185], v[168:169], v[80:81]
	v_pk_mul_f32 v[186:187], v[170:171], v[82:83]
	v_pk_fma_f32 v[184:185], v[172:173], v[84:85], v[184:185]
	v_pk_fma_f32 v[186:187], v[174:175], v[86:87], v[186:187]
	v_pk_fma_f32 v[184:185], v[176:177], v[88:89], v[184:185]
	v_pk_fma_f32 v[186:187], v[178:179], v[90:91], v[186:187]
	v_pk_fma_f32 v[184:185], v[180:181], v[92:93], v[184:185]
	v_pk_fma_f32 v[186:187], v[182:183], v[94:95], v[186:187]
	v_pk_add_f32 v[184:185], v[184:185], v[186:187]
	v_add_f32_e32 v113, v184, v185
	s_waitcnt vmcnt(13)
	v_cvt_pk_f32_fp8_e32 v[168:169], v8
	v_cvt_pk_f32_fp8_sdwa v[170:171], v8 src0_sel:WORD_1
	v_cvt_pk_f32_fp8_e32 v[172:173], v9
	v_cvt_pk_f32_fp8_sdwa v[174:175], v9 src0_sel:WORD_1
	v_cvt_pk_f32_fp8_e32 v[176:177], v10
	v_cvt_pk_f32_fp8_sdwa v[178:179], v10 src0_sel:WORD_1
	v_cvt_pk_f32_fp8_e32 v[180:181], v11
	v_cvt_pk_f32_fp8_sdwa v[182:183], v11 src0_sel:WORD_1
	v_pk_mul_f32 v[184:185], v[168:169], v[80:81]
	v_pk_mul_f32 v[186:187], v[170:171], v[82:83]
	v_pk_fma_f32 v[184:185], v[172:173], v[84:85], v[184:185]
	v_pk_fma_f32 v[186:187], v[174:175], v[86:87], v[186:187]
	v_pk_fma_f32 v[184:185], v[176:177], v[88:89], v[184:185]
	v_pk_fma_f32 v[186:187], v[178:179], v[90:91], v[186:187]
	v_pk_fma_f32 v[184:185], v[180:181], v[92:93], v[184:185]
	v_pk_fma_f32 v[186:187], v[182:183], v[94:95], v[186:187]
	v_pk_add_f32 v[184:185], v[184:185], v[186:187]
	v_add_f32_e32 v114, v184, v185
	s_waitcnt vmcnt(12)
	v_cvt_pk_f32_fp8_e32 v[168:169], v12
	v_cvt_pk_f32_fp8_sdwa v[170:171], v12 src0_sel:WORD_1
	v_cvt_pk_f32_fp8_e32 v[172:173], v13
	v_cvt_pk_f32_fp8_sdwa v[174:175], v13 src0_sel:WORD_1
	v_cvt_pk_f32_fp8_e32 v[176:177], v14
	v_cvt_pk_f32_fp8_sdwa v[178:179], v14 src0_sel:WORD_1
	v_cvt_pk_f32_fp8_e32 v[180:181], v15
	v_cvt_pk_f32_fp8_sdwa v[182:183], v15 src0_sel:WORD_1
	v_pk_mul_f32 v[184:185], v[168:169], v[80:81]
	v_pk_mul_f32 v[186:187], v[170:171], v[82:83]
	v_pk_fma_f32 v[184:185], v[172:173], v[84:85], v[184:185]
	v_pk_fma_f32 v[186:187], v[174:175], v[86:87], v[186:187]
	v_pk_fma_f32 v[184:185], v[176:177], v[88:89], v[184:185]
	v_pk_fma_f32 v[186:187], v[178:179], v[90:91], v[186:187]
	v_pk_fma_f32 v[184:185], v[180:181], v[92:93], v[184:185]
	v_pk_fma_f32 v[186:187], v[182:183], v[94:95], v[186:187]
	v_pk_add_f32 v[184:185], v[184:185], v[186:187]
	v_add_f32_e32 v115, v184, v185
	s_waitcnt vmcnt(11)
	v_cvt_pk_f32_fp8_e32 v[168:169], v16
	v_cvt_pk_f32_fp8_sdwa v[170:171], v16 src0_sel:WORD_1
	v_cvt_pk_f32_fp8_e32 v[172:173], v17
	v_cvt_pk_f32_fp8_sdwa v[174:175], v17 src0_sel:WORD_1
	v_cvt_pk_f32_fp8_e32 v[176:177], v18
	v_cvt_pk_f32_fp8_sdwa v[178:179], v18 src0_sel:WORD_1
	v_cvt_pk_f32_fp8_e32 v[180:181], v19
	v_cvt_pk_f32_fp8_sdwa v[182:183], v19 src0_sel:WORD_1
	v_pk_mul_f32 v[184:185], v[168:169], v[80:81]
	v_pk_mul_f32 v[186:187], v[170:171], v[82:83]
	v_pk_fma_f32 v[184:185], v[172:173], v[84:85], v[184:185]
	v_pk_fma_f32 v[186:187], v[174:175], v[86:87], v[186:187]
	v_pk_fma_f32 v[184:185], v[176:177], v[88:89], v[184:185]
	v_pk_fma_f32 v[186:187], v[178:179], v[90:91], v[186:187]
	v_pk_fma_f32 v[184:185], v[180:181], v[92:93], v[184:185]
	v_pk_fma_f32 v[186:187], v[182:183], v[94:95], v[186:187]
	v_pk_add_f32 v[184:185], v[184:185], v[186:187]
	v_add_f32_e32 v116, v184, v185
	s_waitcnt vmcnt(10)
	v_cvt_pk_f32_fp8_e32 v[168:169], v20
	v_cvt_pk_f32_fp8_sdwa v[170:171], v20 src0_sel:WORD_1
	v_cvt_pk_f32_fp8_e32 v[172:173], v21
	v_cvt_pk_f32_fp8_sdwa v[174:175], v21 src0_sel:WORD_1
	v_cvt_pk_f32_fp8_e32 v[176:177], v22
	v_cvt_pk_f32_fp8_sdwa v[178:179], v22 src0_sel:WORD_1
	v_cvt_pk_f32_fp8_e32 v[180:181], v23
	v_cvt_pk_f32_fp8_sdwa v[182:183], v23 src0_sel:WORD_1
	v_pk_mul_f32 v[184:185], v[168:169], v[80:81]
	v_pk_mul_f32 v[186:187], v[170:171], v[82:83]
	v_pk_fma_f32 v[184:185], v[172:173], v[84:85], v[184:185]
	v_pk_fma_f32 v[186:187], v[174:175], v[86:87], v[186:187]
	v_pk_fma_f32 v[184:185], v[176:177], v[88:89], v[184:185]
	v_pk_fma_f32 v[186:187], v[178:179], v[90:91], v[186:187]
	v_pk_fma_f32 v[184:185], v[180:181], v[92:93], v[184:185]
	v_pk_fma_f32 v[186:187], v[182:183], v[94:95], v[186:187]
	v_pk_add_f32 v[184:185], v[184:185], v[186:187]
	v_add_f32_e32 v117, v184, v185
	s_waitcnt vmcnt(9)
	v_cvt_pk_f32_fp8_e32 v[168:169], v24
	v_cvt_pk_f32_fp8_sdwa v[170:171], v24 src0_sel:WORD_1
	v_cvt_pk_f32_fp8_e32 v[172:173], v25
	v_cvt_pk_f32_fp8_sdwa v[174:175], v25 src0_sel:WORD_1
	v_cvt_pk_f32_fp8_e32 v[176:177], v26
	v_cvt_pk_f32_fp8_sdwa v[178:179], v26 src0_sel:WORD_1
	v_cvt_pk_f32_fp8_e32 v[180:181], v27
	v_cvt_pk_f32_fp8_sdwa v[182:183], v27 src0_sel:WORD_1
	v_pk_mul_f32 v[184:185], v[168:169], v[80:81]
	v_pk_mul_f32 v[186:187], v[170:171], v[82:83]
	v_pk_fma_f32 v[184:185], v[172:173], v[84:85], v[184:185]
	v_pk_fma_f32 v[186:187], v[174:175], v[86:87], v[186:187]
	v_pk_fma_f32 v[184:185], v[176:177], v[88:89], v[184:185]
	v_pk_fma_f32 v[186:187], v[178:179], v[90:91], v[186:187]
	v_pk_fma_f32 v[184:185], v[180:181], v[92:93], v[184:185]
	v_pk_fma_f32 v[186:187], v[182:183], v[94:95], v[186:187]
	v_pk_add_f32 v[184:185], v[184:185], v[186:187]
	v_add_f32_e32 v118, v184, v185
	s_waitcnt vmcnt(8)
	v_cvt_pk_f32_fp8_e32 v[168:169], v28
	v_cvt_pk_f32_fp8_sdwa v[170:171], v28 src0_sel:WORD_1
	v_cvt_pk_f32_fp8_e32 v[172:173], v29
	v_cvt_pk_f32_fp8_sdwa v[174:175], v29 src0_sel:WORD_1
	v_cvt_pk_f32_fp8_e32 v[176:177], v30
	v_cvt_pk_f32_fp8_sdwa v[178:179], v30 src0_sel:WORD_1
	v_cvt_pk_f32_fp8_e32 v[180:181], v31
	v_cvt_pk_f32_fp8_sdwa v[182:183], v31 src0_sel:WORD_1
	v_pk_mul_f32 v[184:185], v[168:169], v[80:81]
	v_pk_mul_f32 v[186:187], v[170:171], v[82:83]
	v_pk_fma_f32 v[184:185], v[172:173], v[84:85], v[184:185]
	v_pk_fma_f32 v[186:187], v[174:175], v[86:87], v[186:187]
	v_pk_fma_f32 v[184:185], v[176:177], v[88:89], v[184:185]
	v_pk_fma_f32 v[186:187], v[178:179], v[90:91], v[186:187]
	v_pk_fma_f32 v[184:185], v[180:181], v[92:93], v[184:185]
	v_pk_fma_f32 v[186:187], v[182:183], v[94:95], v[186:187]
	v_pk_add_f32 v[184:185], v[184:185], v[186:187]
	v_add_f32_e32 v119, v184, v185
	s_waitcnt vmcnt(7)
	v_cvt_pk_f32_fp8_e32 v[168:169], v32
	v_cvt_pk_f32_fp8_sdwa v[170:171], v32 src0_sel:WORD_1
	v_cvt_pk_f32_fp8_e32 v[172:173], v33
	v_cvt_pk_f32_fp8_sdwa v[174:175], v33 src0_sel:WORD_1
	v_cvt_pk_f32_fp8_e32 v[176:177], v34
	v_cvt_pk_f32_fp8_sdwa v[178:179], v34 src0_sel:WORD_1
	v_cvt_pk_f32_fp8_e32 v[180:181], v35
	v_cvt_pk_f32_fp8_sdwa v[182:183], v35 src0_sel:WORD_1
	v_pk_mul_f32 v[184:185], v[168:169], v[80:81]
	v_pk_mul_f32 v[186:187], v[170:171], v[82:83]
	v_pk_fma_f32 v[184:185], v[172:173], v[84:85], v[184:185]
	v_pk_fma_f32 v[186:187], v[174:175], v[86:87], v[186:187]
	v_pk_fma_f32 v[184:185], v[176:177], v[88:89], v[184:185]
	v_pk_fma_f32 v[186:187], v[178:179], v[90:91], v[186:187]
	v_pk_fma_f32 v[184:185], v[180:181], v[92:93], v[184:185]
	v_pk_fma_f32 v[186:187], v[182:183], v[94:95], v[186:187]
	v_pk_add_f32 v[184:185], v[184:185], v[186:187]
	v_add_f32_e32 v120, v184, v185
	s_waitcnt vmcnt(6)
	v_cvt_pk_f32_fp8_e32 v[168:169], v36
	v_cvt_pk_f32_fp8_sdwa v[170:171], v36 src0_sel:WORD_1
	v_cvt_pk_f32_fp8_e32 v[172:173], v37
	v_cvt_pk_f32_fp8_sdwa v[174:175], v37 src0_sel:WORD_1
	v_cvt_pk_f32_fp8_e32 v[176:177], v38
	v_cvt_pk_f32_fp8_sdwa v[178:179], v38 src0_sel:WORD_1
	v_cvt_pk_f32_fp8_e32 v[180:181], v39
	v_cvt_pk_f32_fp8_sdwa v[182:183], v39 src0_sel:WORD_1
	v_pk_mul_f32 v[184:185], v[168:169], v[80:81]
	v_pk_mul_f32 v[186:187], v[170:171], v[82:83]
	v_pk_fma_f32 v[184:185], v[172:173], v[84:85], v[184:185]
	v_pk_fma_f32 v[186:187], v[174:175], v[86:87], v[186:187]
	v_pk_fma_f32 v[184:185], v[176:177], v[88:89], v[184:185]
	v_pk_fma_f32 v[186:187], v[178:179], v[90:91], v[186:187]
	v_pk_fma_f32 v[184:185], v[180:181], v[92:93], v[184:185]
	v_pk_fma_f32 v[186:187], v[182:183], v[94:95], v[186:187]
	v_pk_add_f32 v[184:185], v[184:185], v[186:187]
	v_add_f32_e32 v121, v184, v185
	s_waitcnt vmcnt(5)
	v_cvt_pk_f32_fp8_e32 v[168:169], v40
	v_cvt_pk_f32_fp8_sdwa v[170:171], v40 src0_sel:WORD_1
	v_cvt_pk_f32_fp8_e32 v[172:173], v41
	v_cvt_pk_f32_fp8_sdwa v[174:175], v41 src0_sel:WORD_1
	v_cvt_pk_f32_fp8_e32 v[176:177], v42
	v_cvt_pk_f32_fp8_sdwa v[178:179], v42 src0_sel:WORD_1
	v_cvt_pk_f32_fp8_e32 v[180:181], v43
	v_cvt_pk_f32_fp8_sdwa v[182:183], v43 src0_sel:WORD_1
	v_pk_mul_f32 v[184:185], v[168:169], v[80:81]
	v_pk_mul_f32 v[186:187], v[170:171], v[82:83]
	v_pk_fma_f32 v[184:185], v[172:173], v[84:85], v[184:185]
	v_pk_fma_f32 v[186:187], v[174:175], v[86:87], v[186:187]
	v_pk_fma_f32 v[184:185], v[176:177], v[88:89], v[184:185]
	v_pk_fma_f32 v[186:187], v[178:179], v[90:91], v[186:187]
	v_pk_fma_f32 v[184:185], v[180:181], v[92:93], v[184:185]
	v_pk_fma_f32 v[186:187], v[182:183], v[94:95], v[186:187]
	v_pk_add_f32 v[184:185], v[184:185], v[186:187]
	v_add_f32_e32 v122, v184, v185
	s_waitcnt vmcnt(4)
	v_cvt_pk_f32_fp8_e32 v[168:169], v44
	v_cvt_pk_f32_fp8_sdwa v[170:171], v44 src0_sel:WORD_1
	v_cvt_pk_f32_fp8_e32 v[172:173], v45
	v_cvt_pk_f32_fp8_sdwa v[174:175], v45 src0_sel:WORD_1
	v_cvt_pk_f32_fp8_e32 v[176:177], v46
	v_cvt_pk_f32_fp8_sdwa v[178:179], v46 src0_sel:WORD_1
	v_cvt_pk_f32_fp8_e32 v[180:181], v47
	v_cvt_pk_f32_fp8_sdwa v[182:183], v47 src0_sel:WORD_1
	v_pk_mul_f32 v[184:185], v[168:169], v[80:81]
	v_pk_mul_f32 v[186:187], v[170:171], v[82:83]
	v_pk_fma_f32 v[184:185], v[172:173], v[84:85], v[184:185]
	v_pk_fma_f32 v[186:187], v[174:175], v[86:87], v[186:187]
	v_pk_fma_f32 v[184:185], v[176:177], v[88:89], v[184:185]
	v_pk_fma_f32 v[186:187], v[178:179], v[90:91], v[186:187]
	v_pk_fma_f32 v[184:185], v[180:181], v[92:93], v[184:185]
	v_pk_fma_f32 v[186:187], v[182:183], v[94:95], v[186:187]
	v_pk_add_f32 v[184:185], v[184:185], v[186:187]
	v_add_f32_e32 v123, v184, v185
	s_waitcnt vmcnt(3)
	v_cvt_pk_f32_fp8_e32 v[168:169], v48
	v_cvt_pk_f32_fp8_sdwa v[170:171], v48 src0_sel:WORD_1
	v_cvt_pk_f32_fp8_e32 v[172:173], v49
	v_cvt_pk_f32_fp8_sdwa v[174:175], v49 src0_sel:WORD_1
	v_cvt_pk_f32_fp8_e32 v[176:177], v50
	v_cvt_pk_f32_fp8_sdwa v[178:179], v50 src0_sel:WORD_1
	v_cvt_pk_f32_fp8_e32 v[180:181], v51
	v_cvt_pk_f32_fp8_sdwa v[182:183], v51 src0_sel:WORD_1
	v_pk_mul_f32 v[184:185], v[168:169], v[80:81]
	v_pk_mul_f32 v[186:187], v[170:171], v[82:83]
	v_pk_fma_f32 v[184:185], v[172:173], v[84:85], v[184:185]
	v_pk_fma_f32 v[186:187], v[174:175], v[86:87], v[186:187]
	v_pk_fma_f32 v[184:185], v[176:177], v[88:89], v[184:185]
	v_pk_fma_f32 v[186:187], v[178:179], v[90:91], v[186:187]
	v_pk_fma_f32 v[184:185], v[180:181], v[92:93], v[184:185]
	v_pk_fma_f32 v[186:187], v[182:183], v[94:95], v[186:187]
	v_pk_add_f32 v[184:185], v[184:185], v[186:187]
	v_add_f32_e32 v124, v184, v185
	s_waitcnt vmcnt(2)
	v_cvt_pk_f32_fp8_e32 v[168:169], v52
	v_cvt_pk_f32_fp8_sdwa v[170:171], v52 src0_sel:WORD_1
	v_cvt_pk_f32_fp8_e32 v[172:173], v53
	v_cvt_pk_f32_fp8_sdwa v[174:175], v53 src0_sel:WORD_1
	v_cvt_pk_f32_fp8_e32 v[176:177], v54
	v_cvt_pk_f32_fp8_sdwa v[178:179], v54 src0_sel:WORD_1
	v_cvt_pk_f32_fp8_e32 v[180:181], v55
	v_cvt_pk_f32_fp8_sdwa v[182:183], v55 src0_sel:WORD_1
	v_pk_mul_f32 v[184:185], v[168:169], v[80:81]
	v_pk_mul_f32 v[186:187], v[170:171], v[82:83]
	v_pk_fma_f32 v[184:185], v[172:173], v[84:85], v[184:185]
	v_pk_fma_f32 v[186:187], v[174:175], v[86:87], v[186:187]
	v_pk_fma_f32 v[184:185], v[176:177], v[88:89], v[184:185]
	v_pk_fma_f32 v[186:187], v[178:179], v[90:91], v[186:187]
	v_pk_fma_f32 v[184:185], v[180:181], v[92:93], v[184:185]
	v_pk_fma_f32 v[186:187], v[182:183], v[94:95], v[186:187]
	v_pk_add_f32 v[184:185], v[184:185], v[186:187]
	v_add_f32_e32 v125, v184, v185
	s_waitcnt vmcnt(1)
	v_cvt_pk_f32_fp8_e32 v[168:169], v56
	v_cvt_pk_f32_fp8_sdwa v[170:171], v56 src0_sel:WORD_1
	v_cvt_pk_f32_fp8_e32 v[172:173], v57
	v_cvt_pk_f32_fp8_sdwa v[174:175], v57 src0_sel:WORD_1
	v_cvt_pk_f32_fp8_e32 v[176:177], v58
	v_cvt_pk_f32_fp8_sdwa v[178:179], v58 src0_sel:WORD_1
	v_cvt_pk_f32_fp8_e32 v[180:181], v59
	v_cvt_pk_f32_fp8_sdwa v[182:183], v59 src0_sel:WORD_1
	v_pk_mul_f32 v[184:185], v[168:169], v[80:81]
	v_pk_mul_f32 v[186:187], v[170:171], v[82:83]
	v_pk_fma_f32 v[184:185], v[172:173], v[84:85], v[184:185]
	v_pk_fma_f32 v[186:187], v[174:175], v[86:87], v[186:187]
	v_pk_fma_f32 v[184:185], v[176:177], v[88:89], v[184:185]
	v_pk_fma_f32 v[186:187], v[178:179], v[90:91], v[186:187]
	v_pk_fma_f32 v[184:185], v[180:181], v[92:93], v[184:185]
	v_pk_fma_f32 v[186:187], v[182:183], v[94:95], v[186:187]
	v_pk_add_f32 v[184:185], v[184:185], v[186:187]
	v_add_f32_e32 v126, v184, v185
	s_waitcnt vmcnt(0)
	v_cvt_pk_f32_fp8_e32 v[168:169], v60
	v_cvt_pk_f32_fp8_sdwa v[170:171], v60 src0_sel:WORD_1
	v_cvt_pk_f32_fp8_e32 v[172:173], v61
	v_cvt_pk_f32_fp8_sdwa v[174:175], v61 src0_sel:WORD_1
	v_cvt_pk_f32_fp8_e32 v[176:177], v62
	v_cvt_pk_f32_fp8_sdwa v[178:179], v62 src0_sel:WORD_1
	v_cvt_pk_f32_fp8_e32 v[180:181], v63
	v_cvt_pk_f32_fp8_sdwa v[182:183], v63 src0_sel:WORD_1
	v_pk_mul_f32 v[184:185], v[168:169], v[80:81]
	v_pk_mul_f32 v[186:187], v[170:171], v[82:83]
	v_pk_fma_f32 v[184:185], v[172:173], v[84:85], v[184:185]
	v_pk_fma_f32 v[186:187], v[174:175], v[86:87], v[186:187]
	v_pk_fma_f32 v[184:185], v[176:177], v[88:89], v[184:185]
	v_pk_fma_f32 v[186:187], v[178:179], v[90:91], v[186:187]
	v_pk_fma_f32 v[184:185], v[180:181], v[92:93], v[184:185]
	v_pk_fma_f32 v[186:187], v[182:183], v[94:95], v[186:187]
	v_pk_add_f32 v[184:185], v[184:185], v[186:187]
	v_add_f32_e32 v127, v184, v185
	s_nop 1
	v_add_f32_dpp v160, v112, v112 row_half_mirror row_mask:0xf bank_mask:0x5
	v_add_f32_dpp v160, v113, v113 row_half_mirror row_mask:0xf bank_mask:0xa
	v_add_f32_dpp v161, v114, v114 row_half_mirror row_mask:0xf bank_mask:0x5
	v_add_f32_dpp v161, v115, v115 row_half_mirror row_mask:0xf bank_mask:0xa
	v_add_f32_dpp v162, v116, v116 row_half_mirror row_mask:0xf bank_mask:0x5
	v_add_f32_dpp v162, v117, v117 row_half_mirror row_mask:0xf bank_mask:0xa
	v_add_f32_dpp v163, v118, v118 row_half_mirror row_mask:0xf bank_mask:0x5
	v_add_f32_dpp v163, v119, v119 row_half_mirror row_mask:0xf bank_mask:0xa
	v_add_f32_dpp v164, v120, v120 row_half_mirror row_mask:0xf bank_mask:0x5
	v_add_f32_dpp v164, v121, v121 row_half_mirror row_mask:0xf bank_mask:0xa
	v_add_f32_dpp v165, v122, v122 row_half_mirror row_mask:0xf bank_mask:0x5
	v_add_f32_dpp v165, v123, v123 row_half_mirror row_mask:0xf bank_mask:0xa
	v_add_f32_dpp v166, v124, v124 row_half_mirror row_mask:0xf bank_mask:0x5
	v_add_f32_dpp v166, v125, v125 row_half_mirror row_mask:0xf bank_mask:0xa
	v_add_f32_dpp v167, v126, v126 row_half_mirror row_mask:0xf bank_mask:0x5
	v_add_f32_dpp v167, v127, v127 row_half_mirror row_mask:0xf bank_mask:0xa
	ds_read_b128 v[168:171], v210
	ds_read_b128 v[172:175], v210 offset:16
	s_nop 1
	v_add_f32_dpp v160, v160, v160 quad_perm:[1,0,3,2] row_mask:0xf bank_mask:0xf
	v_add_f32_dpp v161, v161, v161 quad_perm:[1,0,3,2] row_mask:0xf bank_mask:0xf
	v_add_f32_dpp v162, v162, v162 quad_perm:[1,0,3,2] row_mask:0xf bank_mask:0xf
	v_add_f32_dpp v163, v163, v163 quad_perm:[1,0,3,2] row_mask:0xf bank_mask:0xf
	v_add_f32_dpp v164, v164, v164 quad_perm:[1,0,3,2] row_mask:0xf bank_mask:0xf
	v_add_f32_dpp v165, v165, v165 quad_perm:[1,0,3,2] row_mask:0xf bank_mask:0xf
	v_add_f32_dpp v166, v166, v166 quad_perm:[1,0,3,2] row_mask:0xf bank_mask:0xf
	v_add_f32_dpp v167, v167, v167 quad_perm:[1,0,3,2] row_mask:0xf bank_mask:0xf
	s_nop 1
	v_add_f32_dpp v160, v160, v160 quad_perm:[2,3,0,1] row_mask:0xf bank_mask:0xf
	v_add_f32_dpp v161, v161, v161 quad_perm:[2,3,0,1] row_mask:0xf bank_mask:0xf
	v_add_f32_dpp v162, v162, v162 quad_perm:[2,3,0,1] row_mask:0xf bank_mask:0xf
	v_add_f32_dpp v163, v163, v163 quad_perm:[2,3,0,1] row_mask:0xf bank_mask:0xf
	v_add_f32_dpp v164, v164, v164 quad_perm:[2,3,0,1] row_mask:0xf bank_mask:0xf
	v_add_f32_dpp v165, v165, v165 quad_perm:[2,3,0,1] row_mask:0xf bank_mask:0xf
	v_add_f32_dpp v166, v166, v166 quad_perm:[2,3,0,1] row_mask:0xf bank_mask:0xf
	v_add_f32_dpp v167, v167, v167 quad_perm:[2,3,0,1] row_mask:0xf bank_mask:0xf
	s_waitcnt lgkmcnt(0)
	v_add_f32_e32 v168, v168, v160
	v_add_f32_e32 v169, v169, v161
	v_add_f32_e32 v170, v170, v162
	v_add_f32_e32 v171, v171, v163
	v_add_f32_e32 v172, v172, v164
	v_add_f32_e32 v173, v173, v165
	v_add_f32_e32 v174, v174, v166
	v_add_f32_e32 v175, v175, v167
	ds_write_b128 v210, v[168:171]
	ds_write_b128 v210, v[172:175] offset:16
	s_add_i32 s17, s17, 1
	s_cmp_lt_i32 s17, s43
	s_cbranch_scc1 .Lpb_unit
	s_add_i32 s16, s16, 1
	s_cmp_lt_i32 s16, 8
	s_cbranch_scc1 .Lpb_slice
	v_and_b32_e32 v160, 63, v218
	v_and_b32_e32 v161, 0x30, v160
	v_and_b32_e32 v162, 1, v160
	v_bfe_u32 v163, v160, 1, 3
	v_lshl_add_u32 v161, v162, 3, v161
	v_add_u32_e32 v161, v161, v163
	v_lshlrev_b32_e32 v161, 2, v161
	v_lshlrev_b32_e32 v160, 2, v160
	v_sub_u32_e32 v162, v202, v160
	v_add_u32_e32 v161, v161, v162
	v_add_u32_e32 v161, 0x2400, v161
	s_mov_b32 s17, 0

.Lpa_g1:
	s_andn2_saveexec_b64 s[0:1], s[0:1]
	v_mul_f32_e32 v173, v172, v172
	v_fmamk_f32 v176, v173, 0xba1345e1, v199
	v_fmaak_f32 v176, v173, v176, 0xbcdac9b8
	v_fmaak_f32 v176, v173, v176, 0x3de703be
	v_fmaak_f32 v176, v173, v176, 0xbec09330
	v_fmaak_f32 v173, v173, v176, 0x3e0375d0
	v_fma_f32 v173, |v172|, v173, |v172|
	s_or_b64 exec, exec, s[0:1]
	v_bfi_b32 v172, s67, v173, v172
	v_mul_f32_e32 v176, 0.5, v167
	v_add_f32_e32 v172, 1.0, v172
	v_mul_f32_e32 v172, v176, v172
	v_mul_f32_e32 v170, v168, v170
	v_mul_f32_e32 v172, v169, v172
	v_mul_f32_e32 v170, 0x3d000000, v170
	v_mul_f32_e32 v172, 0x3d000000, v172
	ds_write2st64_b32 v165, v170, v172 offset0:18 offset1:19
	ds_write2st64_b32 v164, v203, v203 offset1:1
	s_add_i32 s17, s17, 1
	s_cmp_lt_i32 s17, 8
	s_cbranch_scc1 .Lpa_tok
	s_waitcnt lgkmcnt(0)
	s_barrier
	v_sub_u32_e32 v164, v161, v162
	v_add_u32_e32 v164, 0x2400, v164
	v_add_u32_e32 v165, 0x3640, v164
	v_add_u32_e32 v174, 0x6c80, v164
	v_add_u32_e32 v175, 0xa2c0, v164
	ds_read2st64_b32 v[166:167], v164 offset1:1
	ds_read2st64_b32 v[176:177], v165 offset1:1
	ds_read2st64_b32 v[178:179], v174 offset1:1
	ds_read2st64_b32 v[180:181], v175 offset1:1
	v_add_u32_e32 v165, 0x1000, v202
	ds_read2st64_b32 v[168:169], v165 offset0:18 offset1:19
	s_waitcnt lgkmcnt(0)
	v_add_f32_e32 v166, v166, v176
	v_add_f32_e32 v167, v167, v177
	v_add_f32_e32 v166, v166, v178
	v_add_f32_e32 v167, v167, v179
	v_add_f32_e32 v166, v166, v180
	v_add_f32_e32 v167, v167, v181
	v_mul_f32_e32 v170, 0x3f3504f3, v166
	v_cmp_nlt_f32_e64 s[0:1], |v170|, 1.0
	s_and_saveexec_b64 s[22:23], s[0:1]
	s_xor_b64 s[0:1], exec, s[22:23]
	s_cbranch_execz .Lpa_g2
	v_fma_f32 v171, |v170|, s54, v200
	v_fma_f32 v171, |v170|, v171, s55
	v_fma_f32 v171, |v170|, v171, s56
	v_fma_f32 v171, |v170|, v171, s57
	v_fma_f32 v171, |v170|, v171, s62
	v_fma_f32 v171, |v170|, v171, s63
	v_fma_f32 v171, |v170|, v171, |v170|
	v_mul_f32_e32 v176, 0xbfb8aa3b, v171
	v_fma_f32 v177, v171, s64, -v176
	v_rndne_f32_e32 v178, v176
	v_fmac_f32_e32 v177, 0xb2a5705f, v171
	v_sub_f32_e32 v176, v176, v178
	v_add_f32_e32 v176, v176, v177
	v_cvt_i32_f32_e32 v177, v178
	v_exp_f32_e32 v176, v176
	v_cmp_nlt_f32_e32 vcc, s65, v171
	v_ldexp_f32 v176, v176, v177
	s_nop 0
	v_cndmask_b32_e32 v176, 0, v176, vcc
	v_cmp_ngt_f32_e32 vcc, s66, v171
	s_nop 1
	v_cndmask_b32_e32 v171, v201, v176, vcc
	v_sub_f32_e32 v171, 1.0, v171

.Lpa_g3:
	s_andn2_saveexec_b64 s[0:1], s[0:1]
	v_mul_f32_e32 v173, v172, v172
	v_fmamk_f32 v176, v173, 0xba1345e1, v199
	v_fmaak_f32 v176, v173, v176, 0xbcdac9b8
	v_fmaak_f32 v176, v173, v176, 0x3de703be
	v_fmaak_f32 v176, v173, v176, 0xbec09330
	v_fmaak_f32 v173, v173, v176, 0x3e0375d0
	v_fma_f32 v173, |v172|, v173, |v172|
	s_or_b64 exec, exec, s[0:1]
	v_bfi_b32 v172, s67, v173, v172
	v_mul_f32_e32 v176, 0.5, v167
	v_add_f32_e32 v172, 1.0, v172
	v_mul_f32_e32 v172, v176, v172
	v_mul_f32_e32 v170, v168, v170
	v_mul_f32_e32 v172, v169, v172
	v_mul_f32_e32 v170, 0x3d000000, v170
	v_mul_f32_e32 v172, 0x3d000000, v172
	ds_write2st64_b32 v165, v170, v172 offset0:18 offset1:19
	v_mov_b32_e32 v194, 0
	s_waitcnt lgkmcnt(0)
	s_mov_b32 s16, 0

.Lpc_unit:
	s_lshl_b32 s0, s17, 11
	s_add_i32 s0, s0, s27
	s_cmp_eq_u32 s17, 8
	s_cselect_b32 s0, s44, s0
	s_lshl_b32 s1, s16, 9
	s_lshl_b32 s24, s0, 12
	s_add_u32 s24, s24, s1
	s_add_u32 s20, s4, s24
	s_addc_u32 s21, s5, 0
	s_lshl_b32 s24, s0, 11
	s_lshr_b32 s1, s1, 1
	s_add_u32 s24, s24, s1
	s_add_u32 s36, s12, s24
	s_addc_u32 s37, s13, 0
	s_lshl_b32 s25, s16, 21
	s_add_u32 s18, s10, s25
	s_addc_u32 s19, s11, 0
	s_lshl_b32 s25, s17, 9
	v_add_u32_e32 v205, s25, v190
	v_add_u32_e32 v206, s25, v202
	ds_read_b128 v[64:67], v205
	ds_read_b128 v[68:71], v205 offset:16
	ds_read_b128 v[72:75], v205 offset:32
	ds_read_b128 v[76:79], v205 offset:48
	ds_read_b128 v[112:115], v205 offset:4608
	ds_read_b128 v[116:119], v205 offset:4624
	ds_read_b128 v[120:123], v205 offset:4640
	ds_read_b128 v[124:127], v205 offset:4656
	global_load_dwordx2 v[208:209], v211, s[20:21]
	s_waitcnt lgkmcnt(4)
	v_add_u32_e32 v64, v64, v188
	v_add_u32_e32 v65, v65, v188
	v_add_u32_e32 v66, v66, v188
	v_add_u32_e32 v67, v67, v188
	v_add_u32_e32 v68, v68, v188
	v_add_u32_e32 v69, v69, v188
	v_add_u32_e32 v70, v70, v188
	v_add_u32_e32 v71, v71, v188
	v_add_u32_e32 v72, v72, v188
	v_add_u32_e32 v73, v73, v188
	v_add_u32_e32 v74, v74, v188
	v_add_u32_e32 v75, v75, v188
	v_add_u32_e32 v76, v76, v188
	v_add_u32_e32 v77, v77, v188
	v_add_u32_e32 v78, v78, v188
	v_add_u32_e32 v79, v79, v188
	global_load_dwordx4 v[0:3], v64, s[18:19]
	global_load_dwordx4 v[4:7], v65, s[18:19]
	global_load_dwordx4 v[8:11], v66, s[18:19]
	global_load_dwordx4 v[12:15], v67, s[18:19]
	global_load_dwordx4 v[16:19], v68, s[18:19]
	global_load_dwordx4 v[20:23], v69, s[18:19]
	global_load_dwordx4 v[24:27], v70, s[18:19]
	global_load_dwordx4 v[28:31], v71, s[18:19]
	global_load_dwordx4 v[32:35], v72, s[18:19]
	global_load_dwordx4 v[36:39], v73, s[18:19]
	global_load_dwordx4 v[40:43], v74, s[18:19]
	global_load_dwordx4 v[44:47], v75, s[18:19]
	global_load_dwordx4 v[48:51], v76, s[18:19]
	global_load_dwordx4 v[52:55], v77, s[18:19]
	global_load_dwordx4 v[56:59], v78, s[18:19]
	global_load_dwordx4 v[60:63], v79, s[18:19]
	s_waitcnt lgkmcnt(0)
	s_waitcnt vmcnt(15)
	v_cvt_pk_f32_fp8_e32 v[168:169], v0
	v_cvt_pk_f32_fp8_sdwa v[170:171], v0 src0_sel:WORD_1
	v_cvt_pk_f32_fp8_e32 v[172:173], v1
	v_cvt_pk_f32_fp8_sdwa v[174:175], v1 src0_sel:WORD_1
	v_cvt_pk_f32_fp8_e32 v[176:177], v2
	v_cvt_pk_f32_fp8_sdwa v[178:179], v2 src0_sel:WORD_1
	v_cvt_pk_f32_fp8_e32 v[180:181], v3
	v_cvt_pk_f32_fp8_sdwa v[182:183], v3 src0_sel:WORD_1
	v_pk_mul_f32 v[144:145], v[168:169], v[112:113] op_sel_hi:[1,0]
	v_pk_mul_f32 v[146:147], v[170:171], v[112:113] op_sel_hi:[1,0]
	v_pk_mul_f32 v[148:149], v[172:173], v[112:113] op_sel_hi:[1,0]
	v_pk_mul_f32 v[150:151], v[174:175], v[112:113] op_sel_hi:[1,0]
	v_pk_mul_f32 v[152:153], v[176:177], v[112:113] op_sel_hi:[1,0]
	v_pk_mul_f32 v[154:155], v[178:179], v[112:113] op_sel_hi:[1,0]
	v_pk_mul_f32 v[156:157], v[180:181], v[112:113] op_sel_hi:[1,0]
	v_pk_mul_f32 v[158:159], v[182:183], v[112:113] op_sel_hi:[1,0]
	s_waitcnt vmcnt(14)
	v_cvt_pk_f32_fp8_e32 v[168:169], v4
	v_cvt_pk_f32_fp8_sdwa v[170:171], v4 src0_sel:WORD_1
	v_cvt_pk_f32_fp8_e32 v[172:173], v5
	v_cvt_pk_f32_fp8_sdwa v[174:175], v5 src0_sel:WORD_1
	v_cvt_pk_f32_fp8_e32 v[176:177], v6
	v_cvt_pk_f32_fp8_sdwa v[178:179], v6 src0_sel:WORD_1
	v_cvt_pk_f32_fp8_e32 v[180:181], v7
	v_cvt_pk_f32_fp8_sdwa v[182:183], v7 src0_sel:WORD_1
	v_pk_fma_f32 v[144:145], v[168:169], v[112:113], v[144:145] op_sel:[0,1,0] op_sel_hi:[1,1,1]
	v_pk_fma_f32 v[146:147], v[170:171], v[112:113], v[146:147] op_sel:[0,1,0] op_sel_hi:[1,1,1]
	v_pk_fma_f32 v[148:149], v[172:173], v[112:113], v[148:149] op_sel:[0,1,0] op_sel_hi:[1,1,1]
	v_pk_fma_f32 v[150:151], v[174:175], v[112:113], v[150:151] op_sel:[0,1,0] op_sel_hi:[1,1,1]
	v_pk_fma_f32 v[152:153], v[176:177], v[112:113], v[152:153] op_sel:[0,1,0] op_sel_hi:[1,1,1]
	v_pk_fma_f32 v[154:155], v[178:179], v[112:113], v[154:155] op_sel:[0,1,0] op_sel_hi:[1,1,1]
	v_pk_fma_f32 v[156:157], v[180:181], v[112:113], v[156:157] op_sel:[0,1,0] op_sel_hi:[1,1,1]
	v_pk_fma_f32 v[158:159], v[182:183], v[112:113], v[158:159] op_sel:[0,1,0] op_sel_hi:[1,1,1]
	s_waitcnt vmcnt(13)
	v_cvt_pk_f32_fp8_e32 v[168:169], v8
	v_cvt_pk_f32_fp8_sdwa v[170:171], v8 src0_sel:WORD_1
	v_cvt_pk_f32_fp8_e32 v[172:173], v9
	v_cvt_pk_f32_fp8_sdwa v[174:175], v9 src0_sel:WORD_1
	v_cvt_pk_f32_fp8_e32 v[176:177], v10
	v_cvt_pk_f32_fp8_sdwa v[178:179], v10 src0_sel:WORD_1
	v_cvt_pk_f32_fp8_e32 v[180:181], v11
	v_cvt_pk_f32_fp8_sdwa v[182:183], v11 src0_sel:WORD_1
	v_pk_fma_f32 v[144:145], v[168:169], v[114:115], v[144:145] op_sel_hi:[1,0,1]
	v_pk_fma_f32 v[146:147], v[170:171], v[114:115], v[146:147] op_sel_hi:[1,0,1]
	v_pk_fma_f32 v[148:149], v[172:173], v[114:115], v[148:149] op_sel_hi:[1,0,1]
	v_pk_fma_f32 v[150:151], v[174:175], v[114:115], v[150:151] op_sel_hi:[1,0,1]
	v_pk_fma_f32 v[152:153], v[176:177], v[114:115], v[152:153] op_sel_hi:[1,0,1]
	v_pk_fma_f32 v[154:155], v[178:179], v[114:115], v[154:155] op_sel_hi:[1,0,1]
	v_pk_fma_f32 v[156:157], v[180:181], v[114:115], v[156:157] op_sel_hi:[1,0,1]
	v_pk_fma_f32 v[158:159], v[182:183], v[114:115], v[158:159] op_sel_hi:[1,0,1]
	s_waitcnt vmcnt(12)
	v_cvt_pk_f32_fp8_e32 v[168:169], v12
	v_cvt_pk_f32_fp8_sdwa v[170:171], v12 src0_sel:WORD_1
	v_cvt_pk_f32_fp8_e32 v[172:173], v13
	v_cvt_pk_f32_fp8_sdwa v[174:175], v13 src0_sel:WORD_1
	v_cvt_pk_f32_fp8_e32 v[176:177], v14
	v_cvt_pk_f32_fp8_sdwa v[178:179], v14 src0_sel:WORD_1
	v_cvt_pk_f32_fp8_e32 v[180:181], v15
	v_cvt_pk_f32_fp8_sdwa v[182:183], v15 src0_sel:WORD_1
	v_pk_fma_f32 v[144:145], v[168:169], v[114:115], v[144:145] op_sel:[0,1,0] op_sel_hi:[1,1,1]
	v_pk_fma_f32 v[146:147], v[170:171], v[114:115], v[146:147] op_sel:[0,1,0] op_sel_hi:[1,1,1]
	v_pk_fma_f32 v[148:149], v[172:173], v[114:115], v[148:149] op_sel:[0,1,0] op_sel_hi:[1,1,1]
	v_pk_fma_f32 v[150:151], v[174:175], v[114:115], v[150:151] op_sel:[0,1,0] op_sel_hi:[1,1,1]
	v_pk_fma_f32 v[152:153], v[176:177], v[114:115], v[152:153] op_sel:[0,1,0] op_sel_hi:[1,1,1]
	v_pk_fma_f32 v[154:155], v[178:179], v[114:115], v[154:155] op_sel:[0,1,0] op_sel_hi:[1,1,1]
	v_pk_fma_f32 v[156:157], v[180:181], v[114:115], v[156:157] op_sel:[0,1,0] op_sel_hi:[1,1,1]
	v_pk_fma_f32 v[158:159], v[182:183], v[114:115], v[158:159] op_sel:[0,1,0] op_sel_hi:[1,1,1]
	s_waitcnt vmcnt(11)
	v_cvt_pk_f32_fp8_e32 v[168:169], v16
	v_cvt_pk_f32_fp8_sdwa v[170:171], v16 src0_sel:WORD_1
	v_cvt_pk_f32_fp8_e32 v[172:173], v17
	v_cvt_pk_f32_fp8_sdwa v[174:175], v17 src0_sel:WORD_1
	v_cvt_pk_f32_fp8_e32 v[176:177], v18
	v_cvt_pk_f32_fp8_sdwa v[178:179], v18 src0_sel:WORD_1
	v_cvt_pk_f32_fp8_e32 v[180:181], v19
	v_cvt_pk_f32_fp8_sdwa v[182:183], v19 src0_sel:WORD_1
	v_pk_fma_f32 v[144:145], v[168:169], v[116:117], v[144:145] op_sel_hi:[1,0,1]
	v_pk_fma_f32 v[146:147], v[170:171], v[116:117], v[146:147] op_sel_hi:[1,0,1]
	v_pk_fma_f32 v[148:149], v[172:173], v[116:117], v[148:149] op_sel_hi:[1,0,1]
	v_pk_fma_f32 v[150:151], v[174:175], v[116:117], v[150:151] op_sel_hi:[1,0,1]
	v_pk_fma_f32 v[152:153], v[176:177], v[116:117], v[152:153] op_sel_hi:[1,0,1]
	v_pk_fma_f32 v[154:155], v[178:179], v[116:117], v[154:155] op_sel_hi:[1,0,1]
	v_pk_fma_f32 v[156:157], v[180:181], v[116:117], v[156:157] op_sel_hi:[1,0,1]
	v_pk_fma_f32 v[158:159], v[182:183], v[116:117], v[158:159] op_sel_hi:[1,0,1]
	s_waitcnt vmcnt(10)
	v_cvt_pk_f32_fp8_e32 v[168:169], v20
	v_cvt_pk_f32_fp8_sdwa v[170:171], v20 src0_sel:WORD_1
	v_cvt_pk_f32_fp8_e32 v[172:173], v21
	v_cvt_pk_f32_fp8_sdwa v[174:175], v21 src0_sel:WORD_1
	v_cvt_pk_f32_fp8_e32 v[176:177], v22
	v_cvt_pk_f32_fp8_sdwa v[178:179], v22 src0_sel:WORD_1
	v_cvt_pk_f32_fp8_e32 v[180:181], v23
	v_cvt_pk_f32_fp8_sdwa v[182:183], v23 src0_sel:WORD_1
	v_pk_fma_f32 v[144:145], v[168:169], v[116:117], v[144:145] op_sel:[0,1,0] op_sel_hi:[1,1,1]
	v_pk_fma_f32 v[146:147], v[170:171], v[116:117], v[146:147] op_sel:[0,1,0] op_sel_hi:[1,1,1]
	v_pk_fma_f32 v[148:149], v[172:173], v[116:117], v[148:149] op_sel:[0,1,0] op_sel_hi:[1,1,1]
	v_pk_fma_f32 v[150:151], v[174:175], v[116:117], v[150:151] op_sel:[0,1,0] op_sel_hi:[1,1,1]
	v_pk_fma_f32 v[152:153], v[176:177], v[116:117], v[152:153] op_sel:[0,1,0] op_sel_hi:[1,1,1]
	v_pk_fma_f32 v[154:155], v[178:179], v[116:117], v[154:155] op_sel:[0,1,0] op_sel_hi:[1,1,1]
	v_pk_fma_f32 v[156:157], v[180:181], v[116:117], v[156:157] op_sel:[0,1,0] op_sel_hi:[1,1,1]
	v_pk_fma_f32 v[158:159], v[182:183], v[116:117], v[158:159] op_sel:[0,1,0] op_sel_hi:[1,1,1]
	s_waitcnt vmcnt(9)
	v_cvt_pk_f32_fp8_e32 v[168:169], v24
	v_cvt_pk_f32_fp8_sdwa v[170:171], v24 src0_sel:WORD_1
	v_cvt_pk_f32_fp8_e32 v[172:173], v25
	v_cvt_pk_f32_fp8_sdwa v[174:175], v25 src0_sel:WORD_1
	v_cvt_pk_f32_fp8_e32 v[176:177], v26
	v_cvt_pk_f32_fp8_sdwa v[178:179], v26 src0_sel:WORD_1
	v_cvt_pk_f32_fp8_e32 v[180:181], v27
	v_cvt_pk_f32_fp8_sdwa v[182:183], v27 src0_sel:WORD_1
	v_pk_fma_f32 v[144:145], v[168:169], v[118:119], v[144:145] op_sel_hi:[1,0,1]
	v_pk_fma_f32 v[146:147], v[170:171], v[118:119], v[146:147] op_sel_hi:[1,0,1]
	v_pk_fma_f32 v[148:149], v[172:173], v[118:119], v[148:149] op_sel_hi:[1,0,1]
	v_pk_fma_f32 v[150:151], v[174:175], v[118:119], v[150:151] op_sel_hi:[1,0,1]
	v_pk_fma_f32 v[152:153], v[176:177], v[118:119], v[152:153] op_sel_hi:[1,0,1]
	v_pk_fma_f32 v[154:155], v[178:179], v[118:119], v[154:155] op_sel_hi:[1,0,1]
	v_pk_fma_f32 v[156:157], v[180:181], v[118:119], v[156:157] op_sel_hi:[1,0,1]
	v_pk_fma_f32 v[158:159], v[182:183], v[118:119], v[158:159] op_sel_hi:[1,0,1]
	s_waitcnt vmcnt(8)
	v_cvt_pk_f32_fp8_e32 v[168:169], v28
	v_cvt_pk_f32_fp8_sdwa v[170:171], v28 src0_sel:WORD_1
	v_cvt_pk_f32_fp8_e32 v[172:173], v29
	v_cvt_pk_f32_fp8_sdwa v[174:175], v29 src0_sel:WORD_1
	v_cvt_pk_f32_fp8_e32 v[176:177], v30
	v_cvt_pk_f32_fp8_sdwa v[178:179], v30 src0_sel:WORD_1
	v_cvt_pk_f32_fp8_e32 v[180:181], v31
	v_cvt_pk_f32_fp8_sdwa v[182:183], v31 src0_sel:WORD_1
	v_pk_fma_f32 v[144:145], v[168:169], v[118:119], v[144:145] op_sel:[0,1,0] op_sel_hi:[1,1,1]
	v_pk_fma_f32 v[146:147], v[170:171], v[118:119], v[146:147] op_sel:[0,1,0] op_sel_hi:[1,1,1]
	v_pk_fma_f32 v[148:149], v[172:173], v[118:119], v[148:149] op_sel:[0,1,0] op_sel_hi:[1,1,1]
	v_pk_fma_f32 v[150:151], v[174:175], v[118:119], v[150:151] op_sel:[0,1,0] op_sel_hi:[1,1,1]
	v_pk_fma_f32 v[152:153], v[176:177], v[118:119], v[152:153] op_sel:[0,1,0] op_sel_hi:[1,1,1]
	v_pk_fma_f32 v[154:155], v[178:179], v[118:119], v[154:155] op_sel:[0,1,0] op_sel_hi:[1,1,1]
	v_pk_fma_f32 v[156:157], v[180:181], v[118:119], v[156:157] op_sel:[0,1,0] op_sel_hi:[1,1,1]
	v_pk_fma_f32 v[158:159], v[182:183], v[118:119], v[158:159] op_sel:[0,1,0] op_sel_hi:[1,1,1]
	s_waitcnt vmcnt(7)
	v_cvt_pk_f32_fp8_e32 v[168:169], v32
	v_cvt_pk_f32_fp8_sdwa v[170:171], v32 src0_sel:WORD_1
	v_cvt_pk_f32_fp8_e32 v[172:173], v33
	v_cvt_pk_f32_fp8_sdwa v[174:175], v33 src0_sel:WORD_1
	v_cvt_pk_f32_fp8_e32 v[176:177], v34
	v_cvt_pk_f32_fp8_sdwa v[178:179], v34 src0_sel:WORD_1
	v_cvt_pk_f32_fp8_e32 v[180:181], v35
	v_cvt_pk_f32_fp8_sdwa v[182:183], v35 src0_sel:WORD_1
	v_pk_fma_f32 v[144:145], v[168:169], v[120:121], v[144:145] op_sel_hi:[1,0,1]
	v_pk_fma_f32 v[146:147], v[170:171], v[120:121], v[146:147] op_sel_hi:[1,0,1]
	v_pk_fma_f32 v[148:149], v[172:173], v[120:121], v[148:149] op_sel_hi:[1,0,1]
	v_pk_fma_f32 v[150:151], v[174:175], v[120:121], v[150:151] op_sel_hi:[1,0,1]
	v_pk_fma_f32 v[152:153], v[176:177], v[120:121], v[152:153] op_sel_hi:[1,0,1]
	v_pk_fma_f32 v[154:155], v[178:179], v[120:121], v[154:155] op_sel_hi:[1,0,1]
	v_pk_fma_f32 v[156:157], v[180:181], v[120:121], v[156:157] op_sel_hi:[1,0,1]
	v_pk_fma_f32 v[158:159], v[182:183], v[120:121], v[158:159] op_sel_hi:[1,0,1]
	s_waitcnt vmcnt(6)
	v_cvt_pk_f32_fp8_e32 v[168:169], v36
	v_cvt_pk_f32_fp8_sdwa v[170:171], v36 src0_sel:WORD_1
	v_cvt_pk_f32_fp8_e32 v[172:173], v37
	v_cvt_pk_f32_fp8_sdwa v[174:175], v37 src0_sel:WORD_1
	v_cvt_pk_f32_fp8_e32 v[176:177], v38
	v_cvt_pk_f32_fp8_sdwa v[178:179], v38 src0_sel:WORD_1
	v_cvt_pk_f32_fp8_e32 v[180:181], v39
	v_cvt_pk_f32_fp8_sdwa v[182:183], v39 src0_sel:WORD_1
	v_pk_fma_f32 v[144:145], v[168:169], v[120:121], v[144:145] op_sel:[0,1,0] op_sel_hi:[1,1,1]
	v_pk_fma_f32 v[146:147], v[170:171], v[120:121], v[146:147] op_sel:[0,1,0] op_sel_hi:[1,1,1]
	v_pk_fma_f32 v[148:149], v[172:173], v[120:121], v[148:149] op_sel:[0,1,0] op_sel_hi:[1,1,1]
	v_pk_fma_f32 v[150:151], v[174:175], v[120:121], v[150:151] op_sel:[0,1,0] op_sel_hi:[1,1,1]
	v_pk_fma_f32 v[152:153], v[176:177], v[120:121], v[152:153] op_sel:[0,1,0] op_sel_hi:[1,1,1]
	v_pk_fma_f32 v[154:155], v[178:179], v[120:121], v[154:155] op_sel:[0,1,0] op_sel_hi:[1,1,1]
	v_pk_fma_f32 v[156:157], v[180:181], v[120:121], v[156:157] op_sel:[0,1,0] op_sel_hi:[1,1,1]
	v_pk_fma_f32 v[158:159], v[182:183], v[120:121], v[158:159] op_sel:[0,1,0] op_sel_hi:[1,1,1]
	s_waitcnt vmcnt(5)
	v_cvt_pk_f32_fp8_e32 v[168:169], v40
	v_cvt_pk_f32_fp8_sdwa v[170:171], v40 src0_sel:WORD_1
	v_cvt_pk_f32_fp8_e32 v[172:173], v41
	v_cvt_pk_f32_fp8_sdwa v[174:175], v41 src0_sel:WORD_1
	v_cvt_pk_f32_fp8_e32 v[176:177], v42
	v_cvt_pk_f32_fp8_sdwa v[178:179], v42 src0_sel:WORD_1
	v_cvt_pk_f32_fp8_e32 v[180:181], v43
	v_cvt_pk_f32_fp8_sdwa v[182:183], v43 src0_sel:WORD_1
	v_pk_fma_f32 v[144:145], v[168:169], v[122:123], v[144:145] op_sel_hi:[1,0,1]
	v_pk_fma_f32 v[146:147], v[170:171], v[122:123], v[146:147] op_sel_hi:[1,0,1]
	v_pk_fma_f32 v[148:149], v[172:173], v[122:123], v[148:149] op_sel_hi:[1,0,1]
	v_pk_fma_f32 v[150:151], v[174:175], v[122:123], v[150:151] op_sel_hi:[1,0,1]
	v_pk_fma_f32 v[152:153], v[176:177], v[122:123], v[152:153] op_sel_hi:[1,0,1]
	v_pk_fma_f32 v[154:155], v[178:179], v[122:123], v[154:155] op_sel_hi:[1,0,1]
	v_pk_fma_f32 v[156:157], v[180:181], v[122:123], v[156:157] op_sel_hi:[1,0,1]
	v_pk_fma_f32 v[158:159], v[182:183], v[122:123], v[158:159] op_sel_hi:[1,0,1]
	s_waitcnt vmcnt(4)
	v_cvt_pk_f32_fp8_e32 v[168:169], v44
	v_cvt_pk_f32_fp8_sdwa v[170:171], v44 src0_sel:WORD_1
	v_cvt_pk_f32_fp8_e32 v[172:173], v45
	v_cvt_pk_f32_fp8_sdwa v[174:175], v45 src0_sel:WORD_1
	v_cvt_pk_f32_fp8_e32 v[176:177], v46
	v_cvt_pk_f32_fp8_sdwa v[178:179], v46 src0_sel:WORD_1
	v_cvt_pk_f32_fp8_e32 v[180:181], v47
	v_cvt_pk_f32_fp8_sdwa v[182:183], v47 src0_sel:WORD_1
	v_pk_fma_f32 v[144:145], v[168:169], v[122:123], v[144:145] op_sel:[0,1,0] op_sel_hi:[1,1,1]
	v_pk_fma_f32 v[146:147], v[170:171], v[122:123], v[146:147] op_sel:[0,1,0] op_sel_hi:[1,1,1]
	v_pk_fma_f32 v[148:149], v[172:173], v[122:123], v[148:149] op_sel:[0,1,0] op_sel_hi:[1,1,1]
	v_pk_fma_f32 v[150:151], v[174:175], v[122:123], v[150:151] op_sel:[0,1,0] op_sel_hi:[1,1,1]
	v_pk_fma_f32 v[152:153], v[176:177], v[122:123], v[152:153] op_sel:[0,1,0] op_sel_hi:[1,1,1]
	v_pk_fma_f32 v[154:155], v[178:179], v[122:123], v[154:155] op_sel:[0,1,0] op_sel_hi:[1,1,1]
	v_pk_fma_f32 v[156:157], v[180:181], v[122:123], v[156:157] op_sel:[0,1,0] op_sel_hi:[1,1,1]
	v_pk_fma_f32 v[158:159], v[182:183], v[122:123], v[158:159] op_sel:[0,1,0] op_sel_hi:[1,1,1]
	s_waitcnt vmcnt(3)
	v_cvt_pk_f32_fp8_e32 v[168:169], v48
	v_cvt_pk_f32_fp8_sdwa v[170:171], v48 src0_sel:WORD_1
	v_cvt_pk_f32_fp8_e32 v[172:173], v49
	v_cvt_pk_f32_fp8_sdwa v[174:175], v49 src0_sel:WORD_1
	v_cvt_pk_f32_fp8_e32 v[176:177], v50
	v_cvt_pk_f32_fp8_sdwa v[178:179], v50 src0_sel:WORD_1
	v_cvt_pk_f32_fp8_e32 v[180:181], v51
	v_cvt_pk_f32_fp8_sdwa v[182:183], v51 src0_sel:WORD_1
	v_pk_fma_f32 v[144:145], v[168:169], v[124:125], v[144:145] op_sel_hi:[1,0,1]
	v_pk_fma_f32 v[146:147], v[170:171], v[124:125], v[146:147] op_sel_hi:[1,0,1]
	v_pk_fma_f32 v[148:149], v[172:173], v[124:125], v[148:149] op_sel_hi:[1,0,1]
	v_pk_fma_f32 v[150:151], v[174:175], v[124:125], v[150:151] op_sel_hi:[1,0,1]
	v_pk_fma_f32 v[152:153], v[176:177], v[124:125], v[152:153] op_sel_hi:[1,0,1]
	v_pk_fma_f32 v[154:155], v[178:179], v[124:125], v[154:155] op_sel_hi:[1,0,1]
	v_pk_fma_f32 v[156:157], v[180:181], v[124:125], v[156:157] op_sel_hi:[1,0,1]
	v_pk_fma_f32 v[158:159], v[182:183], v[124:125], v[158:159] op_sel_hi:[1,0,1]
	s_waitcnt vmcnt(2)
	v_cvt_pk_f32_fp8_e32 v[168:169], v52
	v_cvt_pk_f32_fp8_sdwa v[170:171], v52 src0_sel:WORD_1
	v_cvt_pk_f32_fp8_e32 v[172:173], v53
	v_cvt_pk_f32_fp8_sdwa v[174:175], v53 src0_sel:WORD_1
	v_cvt_pk_f32_fp8_e32 v[176:177], v54
	v_cvt_pk_f32_fp8_sdwa v[178:179], v54 src0_sel:WORD_1
	v_cvt_pk_f32_fp8_e32 v[180:181], v55
	v_cvt_pk_f32_fp8_sdwa v[182:183], v55 src0_sel:WORD_1
	v_pk_fma_f32 v[144:145], v[168:169], v[124:125], v[144:145] op_sel:[0,1,0] op_sel_hi:[1,1,1]
	v_pk_fma_f32 v[146:147], v[170:171], v[124:125], v[146:147] op_sel:[0,1,0] op_sel_hi:[1,1,1]
	v_pk_fma_f32 v[148:149], v[172:173], v[124:125], v[148:149] op_sel:[0,1,0] op_sel_hi:[1,1,1]
	v_pk_fma_f32 v[150:151], v[174:175], v[124:125], v[150:151] op_sel:[0,1,0] op_sel_hi:[1,1,1]
	v_pk_fma_f32 v[152:153], v[176:177], v[124:125], v[152:153] op_sel:[0,1,0] op_sel_hi:[1,1,1]
	v_pk_fma_f32 v[154:155], v[178:179], v[124:125], v[154:155] op_sel:[0,1,0] op_sel_hi:[1,1,1]
	v_pk_fma_f32 v[156:157], v[180:181], v[124:125], v[156:157] op_sel:[0,1,0] op_sel_hi:[1,1,1]
	v_pk_fma_f32 v[158:159], v[182:183], v[124:125], v[158:159] op_sel:[0,1,0] op_sel_hi:[1,1,1]
	s_waitcnt vmcnt(1)
	v_cvt_pk_f32_fp8_e32 v[168:169], v56
	v_cvt_pk_f32_fp8_sdwa v[170:171], v56 src0_sel:WORD_1
	v_cvt_pk_f32_fp8_e32 v[172:173], v57
	v_cvt_pk_f32_fp8_sdwa v[174:175], v57 src0_sel:WORD_1
	v_cvt_pk_f32_fp8_e32 v[176:177], v58
	v_cvt_pk_f32_fp8_sdwa v[178:179], v58 src0_sel:WORD_1
	v_cvt_pk_f32_fp8_e32 v[180:181], v59
	v_cvt_pk_f32_fp8_sdwa v[182:183], v59 src0_sel:WORD_1
	v_pk_fma_f32 v[144:145], v[168:169], v[126:127], v[144:145] op_sel_hi:[1,0,1]
	v_pk_fma_f32 v[146:147], v[170:171], v[126:127], v[146:147] op_sel_hi:[1,0,1]
	v_pk_fma_f32 v[148:149], v[172:173], v[126:127], v[148:149] op_sel_hi:[1,0,1]
	v_pk_fma_f32 v[150:151], v[174:175], v[126:127], v[150:151] op_sel_hi:[1,0,1]
	v_pk_fma_f32 v[152:153], v[176:177], v[126:127], v[152:153] op_sel_hi:[1,0,1]
	v_pk_fma_f32 v[154:155], v[178:179], v[126:127], v[154:155] op_sel_hi:[1,0,1]
	v_pk_fma_f32 v[156:157], v[180:181], v[126:127], v[156:157] op_sel_hi:[1,0,1]
	v_pk_fma_f32 v[158:159], v[182:183], v[126:127], v[158:159] op_sel_hi:[1,0,1]
	s_waitcnt vmcnt(0)
	v_cvt_pk_f32_fp8_e32 v[168:169], v60
	v_cvt_pk_f32_fp8_sdwa v[170:171], v60 src0_sel:WORD_1
	v_cvt_pk_f32_fp8_e32 v[172:173], v61
	v_cvt_pk_f32_fp8_sdwa v[174:175], v61 src0_sel:WORD_1
	v_cvt_pk_f32_fp8_e32 v[176:177], v62
	v_cvt_pk_f32_fp8_sdwa v[178:179], v62 src0_sel:WORD_1
	v_cvt_pk_f32_fp8_e32 v[180:181], v63
	v_cvt_pk_f32_fp8_sdwa v[182:183], v63 src0_sel:WORD_1
	v_pk_fma_f32 v[144:145], v[168:169], v[126:127], v[144:145] op_sel:[0,1,0] op_sel_hi:[1,1,1]
	v_pk_fma_f32 v[146:147], v[170:171], v[126:127], v[146:147] op_sel:[0,1,0] op_sel_hi:[1,1,1]
	v_pk_fma_f32 v[148:149], v[172:173], v[126:127], v[148:149] op_sel:[0,1,0] op_sel_hi:[1,1,1]
	v_pk_fma_f32 v[150:151], v[174:175], v[126:127], v[150:151] op_sel:[0,1,0] op_sel_hi:[1,1,1]
	v_pk_fma_f32 v[152:153], v[176:177], v[126:127], v[152:153] op_sel:[0,1,0] op_sel_hi:[1,1,1]
	v_pk_fma_f32 v[154:155], v[178:179], v[126:127], v[154:155] op_sel:[0,1,0] op_sel_hi:[1,1,1]
	v_pk_fma_f32 v[156:157], v[180:181], v[126:127], v[156:157] op_sel:[0,1,0] op_sel_hi:[1,1,1]
	v_pk_fma_f32 v[158:159], v[182:183], v[126:127], v[158:159] op_sel:[0,1,0] op_sel_hi:[1,1,1]
	s_nop 1
	v_permlane32_swap_b32_e32 v144, v152
	v_permlane32_swap_b32_e32 v145, v153
	v_permlane32_swap_b32_e32 v146, v154
	v_permlane32_swap_b32_e32 v147, v155
	v_permlane32_swap_b32_e32 v148, v156
	v_permlane32_swap_b32_e32 v149, v157
	v_permlane32_swap_b32_e32 v150, v158
	v_permlane32_swap_b32_e32 v151, v159
	v_add_f32_e32 v144, v144, v152
	v_add_f32_e32 v145, v145, v153
	v_add_f32_e32 v146, v146, v154
	v_add_f32_e32 v147, v147, v155
	v_add_f32_e32 v148, v148, v156
	v_add_f32_e32 v149, v149, v157
	v_add_f32_e32 v150, v150, v158
	v_add_f32_e32 v151, v151, v159
	v_cndmask_b32_e64 v152, v148, v144, s[38:39]
	v_cndmask_b32_e64 v156, v144, v148, s[38:39]
	v_cndmask_b32_e64 v153, v149, v145, s[38:39]
	v_cndmask_b32_e64 v157, v145, v149, s[38:39]
	v_cndmask_b32_e64 v154, v150, v146, s[38:39]
	v_cndmask_b32_e64 v158, v146, v150, s[38:39]
	v_cndmask_b32_e64 v155, v151, v147, s[38:39]
	v_cndmask_b32_e64 v159, v147, v151, s[38:39]
	ds_bpermute_b32 v152, v138, v152
	ds_bpermute_b32 v153, v138, v153
	ds_bpermute_b32 v154, v138, v154
	ds_bpermute_b32 v155, v138, v155
	s_waitcnt lgkmcnt(0)
	v_add_f32_e32 v144, v156, v152
	v_add_f32_e32 v145, v157, v153
	v_add_f32_e32 v146, v158, v154
	v_add_f32_e32 v147, v159, v155
	s_nop 1
	v_add_f32_dpp v148, v144, v144 row_ror:8 row_mask:0xf bank_mask:0x3
	v_add_f32_dpp v149, v145, v145 row_ror:8 row_mask:0xf bank_mask:0x3
	v_add_f32_dpp v148, v146, v146 row_ror:8 row_mask:0xf bank_mask:0xc
	v_add_f32_dpp v149, v147, v147 row_ror:8 row_mask:0xf bank_mask:0xc
	s_waitcnt vmcnt(0)
	v_add_f32_e32 v208, v208, v148
	v_add_f32_e32 v209, v209, v149
	global_store_dwordx2 v211, v[208:209], s[20:21]
	v_cvt_pk_bf16_f32 v212, v208, v209
	v_mul_f32_e32 v193, v208, v208
	v_fmac_f32_e32 v193, v209, v209
	global_store_dword v213, v212, s[36:37]
	s_cmp_eq_u32 s17, 8
	s_cbranch_scc1 .Lpc_xacc
	ds_add_f32 v206, v193 offset:9216
	s_branch .Lpc_xdone
.Lpc_xacc:
	v_add_f32_e32 v194, v194, v193
.Lpc_xdone:
	s_add_i32 s17, s17, 1
	s_cmp_lt_i32 s17, s43
	s_cbranch_scc1 .Lpc_unit
	s_add_i32 s16, s16, 1
	s_cmp_lt_i32 s16, 8
	s_cbranch_scc1 .Lpc_slice
	s_mov_b32 s17, 0
.Lpd_tok:
	s_lshl_b32 s25, s17, 9
	v_add_u32_e32 v206, s25, v202
	ds_read_b32 v16, v206 offset:9216
	s_lshl_b32 s0, s17, 11
	s_add_i32 s0, s0, s27
	s_lshl_b32 s0, s0, 2
	s_add_u32 s20, s14, s0
	s_addc_u32 s21, s15, 0
	s_waitcnt lgkmcnt(0)
	ds_bpermute_b32 v17, v137, v16
	s_waitcnt lgkmcnt(0)
	v_add_f32_e32 v16, v16, v17
	ds_bpermute_b32 v17, v138, v16
	s_waitcnt lgkmcnt(0)
	v_add_f32_e32 v16, v16, v17
	ds_bpermute_b32 v17, v139, v16
	s_waitcnt lgkmcnt(0)
	v_add_f32_e32 v16, v16, v17
	ds_bpermute_b32 v17, v140, v16
	s_waitcnt lgkmcnt(0)
	v_add_f32_e32 v16, v16, v17
	ds_bpermute_b32 v17, v141, v16
	s_waitcnt lgkmcnt(0)
	v_add_f32_e32 v16, v16, v17
	ds_bpermute_b32 v17, v142, v16
	s_waitcnt lgkmcnt(0)
	v_add_f32_e32 v16, v16, v17
	v_fmamk_f32 v16, v16, 0x3a800000, v198
	v_mul_f32_e32 v17, 0x4b800000, v16
	v_cmp_gt_f32_e32 vcc, s35, v16
	s_nop 1
	v_cndmask_b32_e32 v16, v16, v17, vcc
	v_rsq_f32_e32 v16, v16
	s_nop 0
	v_mul_f32_e32 v17, 0x45800000, v16
	v_cndmask_b32_e32 v18, v16, v17, vcc
	global_store_dword v203, v18, s[20:21]
	s_add_i32 s17, s17, 1
	s_cmp_lt_i32 s17, 8
	s_cbranch_scc1 .Lpd_tok
	ds_bpermute_b32 v17, v137, v194
	s_waitcnt lgkmcnt(0)
	v_add_f32_e32 v194, v194, v17
	ds_bpermute_b32 v17, v138, v194
	s_waitcnt lgkmcnt(0)
	v_add_f32_e32 v194, v194, v17
	ds_bpermute_b32 v17, v139, v194
	s_waitcnt lgkmcnt(0)
	v_add_f32_e32 v194, v194, v17
	ds_bpermute_b32 v17, v140, v194
	s_waitcnt lgkmcnt(0)
	v_add_f32_e32 v194, v194, v17
	ds_bpermute_b32 v17, v141, v194
	s_waitcnt lgkmcnt(0)
	v_add_f32_e32 v194, v194, v17
	ds_bpermute_b32 v17, v142, v194
	s_waitcnt lgkmcnt(0)
	v_add_f32_e32 v194, v194, v17
	v_mov_b32_e32 v16, 0x4a30
	v_lshl_add_u32 v19, v214, 2, v16
	ds_write_b32 v19, v194
	s_waitcnt lgkmcnt(0)
	s_barrier
	ds_read_b128 v[20:23], v16
	s_lshl_b32 s0, s44, 2
	s_add_u32 s20, s14, s0
	s_addc_u32 s21, s15, 0
	s_waitcnt lgkmcnt(0)
	v_add_f32_e32 v16, v20, v21
	v_add_f32_e32 v16, v16, v22
	v_add_f32_e32 v16, v16, v23
	v_fmamk_f32 v16, v16, 0x3a800000, v198
	v_mul_f32_e32 v17, 0x4b800000, v16
	v_cmp_gt_f32_e32 vcc, s35, v16
	s_nop 1
	v_cndmask_b32_e32 v16, v16, v17, vcc
	v_rsq_f32_e32 v16, v16
	s_nop 0
	v_mul_f32_e32 v17, 0x45800000, v16
	v_cndmask_b32_e32 v18, v16, v17, vcc
	global_store_dword v203, v18, s[20:21]
